# FF1 epilogue: fmax canonicalisations in front of the ReLU removed (108 of 483 VALU per tile), store-data pads kept
# baseline (speedup 1.0000x reference)
.LBB0_1454:
	v_lshl_or_b32 v142, s49, 8, v140
	v_lshl_add_u32 v144, s26, 8, v138
	v_ashrrev_i32_e32 v145, 31, v144
	v_max_f32_e32 v120, 0, v120
	v_lshlrev_b64 v[146:147], 14, v[144:145]
	v_mul_f32_e32 v145, v120, v120
	v_max_f32_e32 v120, 0, v125
	v_max_f32_e32 v121, 0, v121
	v_mul_f32_e32 v125, v120, v120
	v_mul_f32_e32 v148, v121, v121
	v_max_f32_e32 v120, 0, v126
	v_max_f32_e32 v121, 0, v122
	v_mul_f32_e32 v149, v120, v120
	v_mul_f32_e32 v150, v121, v121
	v_max_f32_e32 v120, 0, v127
	v_max_f32_e32 v121, 0, v123
	v_ashrrev_i32_e32 v143, 31, v142
	v_max_f32_e32 v124, 0, v124
	v_mul_f32_e32 v123, v120, v120
	v_mul_f32_e32 v151, v121, v121
	v_lshl_add_u64 v[120:121], s[8:9], 0, v[146:147]
	v_lshlrev_b64 v[126:127], 1, v[142:143]
	v_mul_f32_e32 v124, v124, v124
	v_lshl_add_u64 v[120:121], v[120:121], 0, v[126:127]
	v_cvt_pk_bf16_f32 v122, v124, v125
	v_max_f32_e32 v112, 0, v112
	v_max_f32_e32 v113, 0, v113
	v_max_f32_e32 v114, 0, v114
	v_cvt_pk_bf16_f32 v123, v149, v123
	v_cvt_pk_bf16_f32 v124, v145, v148
	v_cvt_pk_bf16_f32 v125, v150, v151
	global_store_dwordx4 v[120:121], v[122:125], off
	s_nop 1
	v_mul_f32_e32 v122, v112, v112
	v_max_f32_e32 v112, v117, v117
	v_mul_f32_e32 v117, v113, v113
	v_max_f32_e32 v113, v118, v118
	v_mul_f32_e32 v118, v114, v114
	v_max_f32_e32 v112, 0, v112
	v_max_f32_e32 v113, 0, v113
	v_max_f32_e32 v114, 0, v119
	v_max_f32_e32 v115, 0, v115
	v_max_f32_e32 v116, 0, v116
	v_mul_f32_e32 v112, v112, v112
	v_mul_f32_e32 v113, v113, v113
	v_mul_f32_e32 v114, v114, v114
	v_mul_f32_e32 v115, v115, v115
	v_mul_f32_e32 v116, v116, v116
	v_cvt_pk_bf16_f32 v112, v116, v112
	v_cvt_pk_bf16_f32 v113, v113, v114
	v_cvt_pk_bf16_f32 v114, v122, v117
	v_cvt_pk_bf16_f32 v115, v118, v115
	v_max_f32_e32 v104, 0, v104
	global_store_dwordx4 v[120:121], v[112:115], off offset:256
	s_nop 0
	v_max_f32_e32 v105, 0, v105
	v_mul_f32_e32 v115, v104, v104
	v_max_f32_e32 v104, 0, v109
	v_mul_f32_e32 v116, v104, v104
	v_mul_f32_e32 v117, v105, v105
	v_or_b32_e32 v112, 16, v144
	v_max_f32_e32 v104, 0, v110
	v_max_f32_e32 v105, 0, v106
	v_ashrrev_i32_e32 v113, 31, v112
	v_mul_f32_e32 v106, v104, v104
	v_mul_f32_e32 v110, v105, v105
	v_lshlrev_b64 v[112:113], 14, v[112:113]
	v_max_f32_e32 v104, 0, v111
	v_max_f32_e32 v105, 0, v107
	v_max_f32_e32 v108, 0, v108
	v_mul_f32_e32 v107, v104, v104
	v_mul_f32_e32 v111, v105, v105
	v_lshl_add_u64 v[104:105], s[8:9], 0, v[112:113]
	v_mul_f32_e32 v114, v108, v108
	v_lshl_add_u64 v[108:109], v[104:105], 0, v[126:127]
	v_cvt_pk_bf16_f32 v104, v114, v116
	v_max_f32_e32 v96, 0, v96
	v_max_f32_e32 v97, 0, v97
	v_max_f32_e32 v98, 0, v98
	v_cvt_pk_bf16_f32 v105, v106, v107
	v_cvt_pk_bf16_f32 v106, v115, v117
	v_cvt_pk_bf16_f32 v107, v110, v111
	global_store_dwordx4 v[108:109], v[104:107], off
	s_nop 1
	v_mul_f32_e32 v104, v96, v96
	v_max_f32_e32 v96, v101, v101
	v_mul_f32_e32 v101, v97, v97
	v_max_f32_e32 v97, v102, v102
	v_mul_f32_e32 v102, v98, v98
	v_max_f32_e32 v96, 0, v96
	v_max_f32_e32 v97, 0, v97
	v_max_f32_e32 v98, 0, v103
	v_max_f32_e32 v99, 0, v99
	v_max_f32_e32 v100, 0, v100
	v_mul_f32_e32 v96, v96, v96
	v_mul_f32_e32 v97, v97, v97
	v_mul_f32_e32 v98, v98, v98
	v_mul_f32_e32 v99, v99, v99
	v_mul_f32_e32 v100, v100, v100
	v_cvt_pk_bf16_f32 v96, v100, v96
	v_cvt_pk_bf16_f32 v97, v97, v98
	v_cvt_pk_bf16_f32 v98, v104, v101
	v_cvt_pk_bf16_f32 v99, v102, v99
	global_store_dwordx4 v[108:109], v[96:99], off offset:256
	s_nop 0
	v_max_f32_e32 v88, 0, v88
	v_mul_f32_e32 v99, v88, v88
	v_max_f32_e32 v88, 0, v93
	v_max_f32_e32 v89, 0, v89
	v_mul_f32_e32 v100, v88, v88
	v_mul_f32_e32 v101, v89, v89
	v_or_b32_e32 v96, 32, v144
	v_max_f32_e32 v88, 0, v94
	v_max_f32_e32 v89, 0, v90
	v_ashrrev_i32_e32 v97, 31, v96
	v_mul_f32_e32 v90, v88, v88
	v_mul_f32_e32 v94, v89, v89
	v_lshlrev_b64 v[96:97], 14, v[96:97]
	v_max_f32_e32 v88, 0, v95
	v_max_f32_e32 v89, 0, v91
	v_max_f32_e32 v92, 0, v92
	v_mul_f32_e32 v91, v88, v88
	v_mul_f32_e32 v95, v89, v89
	v_lshl_add_u64 v[88:89], s[8:9], 0, v[96:97]
	v_mul_f32_e32 v98, v92, v92
	v_lshl_add_u64 v[92:93], v[88:89], 0, v[126:127]
	v_cvt_pk_bf16_f32 v88, v98, v100
	v_max_f32_e32 v80, 0, v80
	v_max_f32_e32 v81, 0, v81
	v_max_f32_e32 v82, 0, v82
	v_cvt_pk_bf16_f32 v89, v90, v91
	v_cvt_pk_bf16_f32 v90, v99, v101
	v_cvt_pk_bf16_f32 v91, v94, v95
	global_store_dwordx4 v[92:93], v[88:91], off
	s_nop 1
	v_mul_f32_e32 v88, v80, v80
	v_max_f32_e32 v80, v85, v85
	v_mul_f32_e32 v85, v81, v81
	v_max_f32_e32 v81, v86, v86
	v_mul_f32_e32 v86, v82, v82
	v_max_f32_e32 v80, 0, v80
	v_max_f32_e32 v81, 0, v81
	v_max_f32_e32 v82, 0, v87
	v_max_f32_e32 v83, 0, v83
	v_max_f32_e32 v84, 0, v84
	v_mul_f32_e32 v80, v80, v80
	v_mul_f32_e32 v81, v81, v81
	v_mul_f32_e32 v82, v82, v82
	v_mul_f32_e32 v83, v83, v83
	v_mul_f32_e32 v84, v84, v84
	v_cvt_pk_bf16_f32 v80, v84, v80
	v_cvt_pk_bf16_f32 v81, v81, v82
	v_cvt_pk_bf16_f32 v82, v88, v85
	v_cvt_pk_bf16_f32 v83, v86, v83
	v_max_f32_e32 v72, 0, v72
	global_store_dwordx4 v[92:93], v[80:83], off offset:256
	s_nop 0
	v_max_f32_e32 v73, 0, v73
	v_mul_f32_e32 v83, v72, v72
	v_max_f32_e32 v72, 0, v77
	v_mul_f32_e32 v84, v72, v72
	v_mul_f32_e32 v85, v73, v73
	v_or_b32_e32 v80, 48, v144
	v_max_f32_e32 v72, 0, v78
	v_max_f32_e32 v73, 0, v74
	v_ashrrev_i32_e32 v81, 31, v80
	v_mul_f32_e32 v74, v72, v72
	v_mul_f32_e32 v78, v73, v73
	v_lshlrev_b64 v[80:81], 14, v[80:81]
	v_max_f32_e32 v72, 0, v79
	v_max_f32_e32 v73, 0, v75
	v_max_f32_e32 v76, 0, v76
	v_mul_f32_e32 v75, v72, v72
	v_mul_f32_e32 v79, v73, v73
	v_lshl_add_u64 v[72:73], s[8:9], 0, v[80:81]
	v_mul_f32_e32 v82, v76, v76
	v_lshl_add_u64 v[76:77], v[72:73], 0, v[126:127]
	v_cvt_pk_bf16_f32 v72, v82, v84
	v_max_f32_e32 v64, 0, v64
	v_max_f32_e32 v65, 0, v65
	v_max_f32_e32 v66, 0, v66
	v_cvt_pk_bf16_f32 v73, v74, v75
	v_cvt_pk_bf16_f32 v74, v83, v85
	v_cvt_pk_bf16_f32 v75, v78, v79
	global_store_dwordx4 v[76:77], v[72:75], off
	s_nop 1
	v_mul_f32_e32 v72, v64, v64
	v_max_f32_e32 v64, v69, v69
	v_mul_f32_e32 v69, v65, v65
	v_max_f32_e32 v65, v70, v70
	v_mul_f32_e32 v70, v66, v66
	v_max_f32_e32 v64, 0, v64
	v_max_f32_e32 v65, 0, v65
	v_max_f32_e32 v66, 0, v71
	v_max_f32_e32 v67, 0, v67
	v_max_f32_e32 v68, 0, v68
	v_mul_f32_e32 v64, v64, v64
	v_mul_f32_e32 v65, v65, v65
	v_mul_f32_e32 v66, v66, v66
	v_mul_f32_e32 v67, v67, v67
	v_mul_f32_e32 v68, v68, v68
	v_cvt_pk_bf16_f32 v64, v68, v64
	v_cvt_pk_bf16_f32 v65, v65, v66
	v_cvt_pk_bf16_f32 v66, v72, v69
	v_cvt_pk_bf16_f32 v67, v70, v67
	global_store_dwordx4 v[76:77], v[64:67], off offset:256
	v_max_f32_e32 v56, 0, v56
	v_max_f32_e32 v57, 0, v57
	v_max_f32_e32 v58, 0, v58
	v_mul_f32_e32 v65, v56, v56
	v_mul_f32_e32 v66, v57, v57
	v_max_f32_e32 v57, v62, v62
	v_mul_f32_e32 v62, v58, v58
	v_max_f32_e32 v56, 0, v61
	v_max_f32_e32 v57, 0, v57
	v_max_f32_e32 v58, 0, v63
	v_max_f32_e32 v59, 0, v59
	v_max_f32_e32 v60, 0, v60
	v_mul_f32_e32 v56, v56, v56
	v_mul_f32_e32 v57, v57, v57
	v_mul_f32_e32 v58, v58, v58
	v_mul_f32_e32 v59, v59, v59
	s_mov_b32 s13, 0x200000
	v_mul_f32_e32 v64, v60, v60
	v_cvt_pk_bf16_f32 v56, v64, v56
	v_cvt_pk_bf16_f32 v57, v57, v58
	v_cvt_pk_bf16_f32 v58, v65, v66
	v_cvt_pk_bf16_f32 v59, v62, v59
	v_add_co_u32_e32 v62, vcc, s13, v120
	v_addc_co_u32_e32 v63, vcc, 0, v121, vcc
	v_max_f32_e32 v48, 0, v48
	v_max_f32_e32 v49, 0, v49
	v_max_f32_e32 v50, 0, v50
	global_store_dwordx4 v[62:63], v[56:59], off
	s_nop 1
	v_mul_f32_e32 v56, v48, v48
	v_max_f32_e32 v48, v53, v53
	v_mul_f32_e32 v53, v49, v49
	v_max_f32_e32 v49, v54, v54
	v_mul_f32_e32 v54, v50, v50
	v_max_f32_e32 v48, 0, v48
	v_max_f32_e32 v49, 0, v49
	v_max_f32_e32 v50, 0, v55
	s_mov_b64 s[28:29], 0x200000
	v_max_f32_e32 v52, 0, v52
	v_mul_f32_e32 v48, v48, v48
	v_mul_f32_e32 v49, v49, v49
	v_max_f32_e32 v51, 0, v51
	v_mul_f32_e32 v50, v50, v50
	v_lshl_add_u64 v[60:61], v[120:121], 0, s[28:29]
	v_mul_f32_e32 v52, v52, v52
	v_mul_f32_e32 v51, v51, v51
	v_cvt_pk_bf16_f32 v48, v52, v48
	v_cvt_pk_bf16_f32 v49, v49, v50
	v_cvt_pk_bf16_f32 v50, v56, v53
	v_max_f32_e32 v40, 0, v40
	v_max_f32_e32 v41, 0, v41
	v_max_f32_e32 v42, 0, v42
	v_cvt_pk_bf16_f32 v51, v54, v51
	global_store_dwordx4 v[60:61], v[48:51], off offset:256
	s_nop 1
	v_mul_f32_e32 v49, v40, v40
	v_mul_f32_e32 v50, v41, v41
	v_max_f32_e32 v41, v46, v46
	v_mul_f32_e32 v46, v42, v42
	v_max_f32_e32 v40, 0, v45
	v_max_f32_e32 v41, 0, v41
	v_max_f32_e32 v42, 0, v47
	v_max_f32_e32 v43, 0, v43
	v_max_f32_e32 v44, 0, v44
	v_mul_f32_e32 v40, v40, v40
	v_mul_f32_e32 v41, v41, v41
	v_mul_f32_e32 v42, v42, v42
	v_mul_f32_e32 v43, v43, v43
	s_mov_b32 s13, 0x240000
	v_mul_f32_e32 v48, v44, v44
	v_cvt_pk_bf16_f32 v40, v48, v40
	v_cvt_pk_bf16_f32 v41, v41, v42
	v_cvt_pk_bf16_f32 v42, v49, v50
	v_cvt_pk_bf16_f32 v43, v46, v43
	v_add_co_u32_e32 v46, vcc, s13, v120
	v_addc_co_u32_e32 v47, vcc, 0, v121, vcc
	v_max_f32_e32 v32, 0, v32
	v_max_f32_e32 v33, 0, v33
	v_max_f32_e32 v34, 0, v34
	global_store_dwordx4 v[46:47], v[40:43], off
	s_nop 0
	s_mov_b64 s[28:29], 0x240000
	v_mul_f32_e32 v40, v32, v32
	v_max_f32_e32 v32, v37, v37
	v_mul_f32_e32 v37, v33, v33
	v_max_f32_e32 v33, v38, v38
	v_mul_f32_e32 v38, v34, v34
	v_max_f32_e32 v32, 0, v32
	v_max_f32_e32 v33, 0, v33
	v_max_f32_e32 v34, 0, v39
	v_max_f32_e32 v35, 0, v35
	v_lshl_add_u64 v[44:45], v[120:121], 0, s[28:29]
	v_max_f32_e32 v36, 0, v36
	v_mul_f32_e32 v32, v32, v32
	v_mul_f32_e32 v33, v33, v33
	v_mul_f32_e32 v34, v34, v34
	v_mul_f32_e32 v35, v35, v35
	v_mul_f32_e32 v36, v36, v36
	v_cvt_pk_bf16_f32 v32, v36, v32
	v_cvt_pk_bf16_f32 v33, v33, v34
	v_cvt_pk_bf16_f32 v34, v40, v37
	v_cvt_pk_bf16_f32 v35, v38, v35
	global_store_dwordx4 v[44:45], v[32:35], off offset:256
	v_max_f32_e32 v24, 0, v24
	v_max_f32_e32 v25, 0, v25
	v_max_f32_e32 v26, 0, v26
	v_mul_f32_e32 v33, v24, v24
	v_mul_f32_e32 v34, v25, v25
	v_max_f32_e32 v25, v30, v30
	v_mul_f32_e32 v30, v26, v26
	v_max_f32_e32 v24, 0, v29
	v_max_f32_e32 v25, 0, v25
	v_max_f32_e32 v26, 0, v31
	v_max_f32_e32 v27, 0, v27
	v_max_f32_e32 v28, 0, v28
	v_mul_f32_e32 v24, v24, v24
	v_mul_f32_e32 v25, v25, v25
	v_mul_f32_e32 v26, v26, v26
	v_mul_f32_e32 v27, v27, v27
	s_mov_b32 s13, 0x280000
	v_mul_f32_e32 v32, v28, v28
	v_cvt_pk_bf16_f32 v24, v32, v24
	v_cvt_pk_bf16_f32 v25, v25, v26
	v_cvt_pk_bf16_f32 v26, v33, v34
	v_cvt_pk_bf16_f32 v27, v30, v27
	v_add_co_u32_e32 v30, vcc, s13, v120
	v_addc_co_u32_e32 v31, vcc, 0, v121, vcc
	v_max_f32_e32 v16, 0, v16
	v_max_f32_e32 v17, 0, v17
	v_max_f32_e32 v18, 0, v18
	global_store_dwordx4 v[30:31], v[24:27], off
	s_nop 1
	v_mul_f32_e32 v24, v16, v16
	v_max_f32_e32 v16, v21, v21
	v_mul_f32_e32 v21, v17, v17
	v_max_f32_e32 v17, v22, v22
	v_mul_f32_e32 v22, v18, v18
	v_max_f32_e32 v16, 0, v16
	v_max_f32_e32 v17, 0, v17
	v_max_f32_e32 v18, 0, v23
	s_mov_b64 s[28:29], 0x280000
	v_max_f32_e32 v20, 0, v20
	v_mul_f32_e32 v16, v16, v16
	v_mul_f32_e32 v17, v17, v17
	v_max_f32_e32 v19, 0, v19
	v_mul_f32_e32 v18, v18, v18
	v_lshl_add_u64 v[28:29], v[120:121], 0, s[28:29]
	v_mul_f32_e32 v20, v20, v20
	v_mul_f32_e32 v19, v19, v19
	v_cvt_pk_bf16_f32 v16, v20, v16
	v_cvt_pk_bf16_f32 v17, v17, v18
	v_cvt_pk_bf16_f32 v18, v24, v21
	v_max_f32_e32 v8, 0, v8
	v_max_f32_e32 v9, 0, v9
	v_max_f32_e32 v10, 0, v10
	v_cvt_pk_bf16_f32 v19, v22, v19
	global_store_dwordx4 v[28:29], v[16:19], off offset:256
	s_nop 1
	v_mul_f32_e32 v17, v8, v8
	v_mul_f32_e32 v18, v9, v9
	v_max_f32_e32 v9, v14, v14
	v_mul_f32_e32 v14, v10, v10
	v_max_f32_e32 v8, 0, v13
	v_max_f32_e32 v9, 0, v9
	v_max_f32_e32 v10, 0, v15
	v_max_f32_e32 v11, 0, v11
	v_max_f32_e32 v12, 0, v12
	v_mul_f32_e32 v8, v8, v8
	v_mul_f32_e32 v9, v9, v9
	v_mul_f32_e32 v10, v10, v10
	v_mul_f32_e32 v11, v11, v11
	s_mov_b32 s13, 0x2c0000
	v_mul_f32_e32 v16, v12, v12
	v_cvt_pk_bf16_f32 v8, v16, v8
	v_cvt_pk_bf16_f32 v9, v9, v10
	v_cvt_pk_bf16_f32 v10, v17, v18
	v_cvt_pk_bf16_f32 v11, v14, v11
	v_add_co_u32_e32 v14, vcc, s13, v120
	v_addc_co_u32_e32 v15, vcc, 0, v121, vcc
	v_max_f32_e32 v0, 0, v0
	v_max_f32_e32 v1, 0, v1
	v_max_f32_e32 v2, 0, v2
	global_store_dwordx4 v[14:15], v[8:11], off
	s_nop 0
	s_mov_b64 s[28:29], 0x2c0000
	v_mul_f32_e32 v8, v0, v0
	v_max_f32_e32 v0, v5, v5
	v_mul_f32_e32 v5, v1, v1
	v_max_f32_e32 v1, v6, v6
	v_mul_f32_e32 v6, v2, v2
	v_max_f32_e32 v0, 0, v0
	v_max_f32_e32 v1, 0, v1
	v_max_f32_e32 v2, 0, v7
	v_max_f32_e32 v3, 0, v3
	v_lshl_add_u64 v[12:13], v[120:121], 0, s[28:29]
	v_max_f32_e32 v4, 0, v4
	v_mul_f32_e32 v0, v0, v0
	v_mul_f32_e32 v1, v1, v1
	v_mul_f32_e32 v2, v2, v2
	v_mul_f32_e32 v3, v3, v3
	v_mul_f32_e32 v4, v4, v4
	v_cvt_pk_bf16_f32 v0, v4, v0
	v_cvt_pk_bf16_f32 v1, v1, v2
	v_cvt_pk_bf16_f32 v2, v8, v5
	v_cvt_pk_bf16_f32 v3, v6, v3
	global_store_dwordx4 v[12:13], v[0:3], off offset:256
	s_andn2_b64 vcc, exec, s[2:3]
	s_mov_b64 s[2:3], -1
	s_cbranch_vccnz .LBB0_1447
	s_andn2_b64 vcc, exec, s[4:5]
	s_cbranch_vccnz .LBB0_1446
	s_barrier
	s_branch .LBB0_1446
